# v109: v107 + 64-byte alignment (.p2align 6) of the hot branch targets of the differential-head loop (.Lm1_fast, .Lm1_fastB, loop tail)
# speedup vs baseline: 1.0268x; 1.0268x over previous
; #define ATT_PV(v_, p_) do { const bf16x8 pf_ = __builtin_bit_cast(bf16x8, (p_)); _Pragma("unroll") for (int d = 0; d < 4; ++d) { \
;         const bf16x8 vf_ = __builtin_shufflevector((v_)[2 * d], (v_)[2 * d + 1], 0, 1, 2, 3, 4, 5, 6, 7); O[d] = MFMA32(vf_, pf_, O[d]); } } while (0)
; template <int MODE>
; __device__ __forceinline__ void attn_unit(const Params& P, LAS unsigned char* lds, const int b, const int h, const int qb) {
;     ...
;             softmax_tile<ONLINE, 4>(s, m1, l1, O, pk1);
;             if constexpr (MODE == 1) {
;                 v_issue<2>(vc, vaddr); v_wait<15>(va); ATT_PV(va, pk1[0]); v_issue<3>(vd, vaddr); v_wait<15>(vb); ATT_PV(vb, pk1[1]); v_wait<8>(vc); ATT_PV(vc, pk1[2]); v_wait<0>(vd); ATT_PV(vd, pk1[3]);
.Lm1_tail_nodma:
	v_mfma_f32_32x32x16_bf16 v[64:79], v[104:107], v[84:87], v[64:79]
	v_mfma_f32_32x32x16_bf16 v[48:63], v[96:99], v[84:87], v[48:63]
	v_mfma_f32_32x32x16_bf16 v[32:47], v[92:95], v[84:87], v[32:47]
	v_mfma_f32_32x32x16_bf16 v[16:31], v[88:91], v[84:87], v[16:31]
	v_mfma_f32_32x32x16_bf16 v[64:79], v[140:143], v[80:83], v[64:79]
	v_mfma_f32_32x32x16_bf16 v[48:63], v[136:139], v[80:83], v[48:63]
	v_mfma_f32_32x32x16_bf16 v[32:47], v[132:135], v[80:83], v[32:47]
	v_mfma_f32_32x32x16_bf16 v[16:31], v[108:111], v[80:83], v[16:31]
	.p2align 6

; #define ATT_WAITV(n) asm volatile("s_waitcnt vmcnt(" #n ")" ::: "memory")
; template <int MODE>
; __device__ __forceinline__ void attn_unit(const Params& P, LAS unsigned char* lds, const int b, const int h, const int qb) {
;     ...
;     for (int kt = kt0; kt < nt; ++kt) {
;         const int rel = kt - kt0, cur = rel & (AL_NBUF - 1);
;         if (kt + 2 < nt) { if (FOX) ATT_WAITV(10); else ATT_WAITV(8); } else if (kt + 1 < nt) { if (FOX) ATT_WAITV(5); else ATT_WAITV(4); } else ATT_WAITV(0);
;         __builtin_amdgcn_s_barrier(); asm volatile("" ::: "memory");
;         if (kt + AL_PD < nt) ATT_DMA(kt + AL_PD, (rel + AL_PD) & (AL_NBUF - 1));
.Lm1_skip:
	s_cmpk_gt_u32 s58, 0xff
	s_cbranch_scc1 .LBB0_474
	s_barrier
	s_add_i32 s41, s40, 3
	s_cmp_ge_u32 s41, s22
	s_cbranch_scc1 .LBB0_474
	s_cmpk_gt_u32 s58, 0xff
	s_cbranch_scc1 .LBB0_474
	s_mov_b64 s[70:71], 0x1000
	s_add_i32 s41, s38, 0x18000
	s_and_b32 s41, s41, 0x18000
	s_add_i32 s41, s77, s41
	v_lshl_add_u64 v[2:3], v[152:153], 0, s[68:69]
	v_lshl_add_u64 v[4:5], v[2:3], 0, s[42:43]
	s_mov_b32 m0, s41
	v_lshl_add_u64 v[2:3], v[2:3], 0, s[44:45]
	global_load_lds_dwordx4 v[4:5], off
	s_add_i32 m0, s41, 0x1000
	v_lshl_add_u64 v[4:5], v[4:5], 0, s[70:71]
	global_load_lds_dwordx4 v[4:5], off
	s_add_i32 m0, s41, 0x2000
	v_lshl_add_u64 v[4:5], v[2:3], 0, s[70:71]
	global_load_lds_dwordx4 v[2:3], off
	s_add_i32 m0, s41, 0x3000
	v_lshl_add_u64 v[2:3], v[154:155], 0, s[68:69]
	global_load_lds_dwordx4 v[4:5], off
	v_lshl_add_u64 v[4:5], v[2:3], 0, s[48:49]
	s_add_i32 m0, s41, 0x4000
	v_lshl_add_u64 v[2:3], v[2:3], 0, s[50:51]
	global_load_lds_dwordx4 v[4:5], off
	s_add_i32 m0, s41, 0x5000
	v_lshl_add_u64 v[4:5], v[4:5], 0, s[70:71]
	global_load_lds_dwordx4 v[4:5], off
	s_add_i32 m0, s41, 0x6000
	v_lshl_add_u64 v[4:5], v[2:3], 0, s[70:71]
	global_load_lds_dwordx4 v[2:3], off
	s_add_i32 m0, s41, 0x7000
	s_nop 0
	global_load_lds_dwordx4 v[4:5], off
	s_branch .LBB0_474
	.p2align 6

; #define ATT_PV(v_, p_) do { const bf16x8 pf_ = __builtin_bit_cast(bf16x8, (p_)); _Pragma("unroll") for (int d = 0; d < 4; ++d) { \
;         const bf16x8 vf_ = __builtin_shufflevector((v_)[2 * d], (v_)[2 * d + 1], 0, 1, 2, 3, 4, 5, 6, 7); O[d] = MFMA32(vf_, pf_, O[d]); } } while (0)
; template <bool ONLINE, int NO>
; __device__ __forceinline__ void softmax_tile(f32x16 (&s)[2], float& m, float& l, f32x16 (&O)[NO], u32x4 (&pk)[4]) {
;     ...
;     float ps = 0.f;
; #pragma unroll
;     for (int blk = 0; blk < 2; ++blk)
; #pragma unroll
;         for (int i = 0; i < 16; ++i) { const float p = __builtin_amdgcn_exp2f(ONLINE ? (s[blk][i] - mn) : s[blk][i]); ps += p; s[blk][i] = p; }
;     l += ps;
; template <int MODE>
; __device__ __forceinline__ void attn_unit(const Params& P, LAS unsigned char* lds, const int b, const int h, const int qb) {
;     ...
;             softmax_tile<ONLINE, 4>(s, m1, l1, O, pk1);
;             if constexpr (MODE == 1) {
;                 v_issue<2>(vc, vaddr); v_wait<15>(va); ATT_PV(va, pk1[0]); v_issue<3>(vd, vaddr); v_wait<15>(vb); ATT_PV(vb, pk1[1]); v_wait<8>(vc); ATT_PV(vc, pk1[2]); v_wait<0>(vd); ATT_PV(vd, pk1[3]);
.Lm1f_nodma:
	v_mfma_f32_32x32x16_bf16 v[64:79], v[144:147], v[84:87], v[64:79]
	v_add_f32_e32 v14, v104, v14
	v_add_f32_e32 v14, v105, v14
	v_add_f32_e32 v14, v106, v14
	v_add_f32_e32 v14, v107, v14
	v_add_f32_e32 v14, v108, v14
	v_add_f32_e32 v14, v109, v14
	v_mfma_f32_32x32x16_bf16 v[48:63], v[140:143], v[84:87], v[48:63]
	v_add_f32_e32 v14, v110, v14
	v_add_f32_e32 v14, v111, v14
	v_add_f32_e32 v14, v2, v14
	v_add_f32_e32 v14, v3, v14
	v_add_f32_e32 v14, v4, v14
	v_add_f32_e32 v14, v5, v14
	v_mfma_f32_32x32x16_bf16 v[32:47], v[136:139], v[84:87], v[32:47]
	v_add_f32_e32 v14, v10, v14
	v_add_f32_e32 v14, v11, v14
	v_add_f32_e32 v14, v12, v14
	v_add_f32_e32 v14, v13, v14
	v_add_f32_e32 v163, v163, v14
	v_mfma_f32_32x32x16_bf16 v[16:31], v[132:135], v[84:87], v[16:31]
	s_branch .LBB0_474

; #define ATT_PV(v_, p_) do { const bf16x8 pf_ = __builtin_bit_cast(bf16x8, (p_)); _Pragma("unroll") for (int d = 0; d < 4; ++d) { \
;         const bf16x8 vf_ = __builtin_shufflevector((v_)[2 * d], (v_)[2 * d + 1], 0, 1, 2, 3, 4, 5, 6, 7); O[d] = MFMA32(vf_, pf_, O[d]); } } while (0)
; template <int MODE>
; __device__ __forceinline__ void attn_unit(const Params& P, LAS unsigned char* lds, const int b, const int h, const int qb) {
;     ...
;             softmax_tile<ONLINE, 4>(s, m1, l1, O, pk1);
;             if constexpr (MODE == 1) {
;                 v_issue<2>(vc, vaddr); v_wait<15>(va); ATT_PV(va, pk1[0]); v_issue<3>(vd, vaddr); v_wait<15>(vb); ATT_PV(vb, pk1[1]); v_wait<8>(vc); ATT_PV(vc, pk1[2]); v_wait<0>(vd); ATT_PV(vd, pk1[3]);
	.p2align 6
